# ATTN: one static s_setprio 1 for waves 4-7 across the phase; remaining packed f32 ops in the ATTN item code unpacked
# speedup vs baseline: 1.0020x; 1.0020x over previous
.LBB0_1259:
	s_cmp_lt_i32 s46, 11
	s_cselect_b64 s[2:3], -1, 0
	s_and_b64 s[8:9], s[2:3], s[0:1]
	s_andn2_b64 vcc, exec, s[8:9]
	s_cbranch_vccnz .LBB0_1478
	s_mov_b32 s0, -1
	v_writelane_b32 v254, s0, 1
	v_mov_b32_e32 v107, v188
	s_movk_i32 s0, 0x80
	s_nop 0
	v_readfirstlane_b32 s6, v107
	v_cmp_gt_i32_e32 vcc, s0, v107
	s_cmpk_lt_u32 s6, 0x100
	s_cbranch_scc1 .Lfa_prio_done
	s_setprio 1
.Lfa_prio_done:
	s_and_saveexec_b64 s[2:3], vcc
	s_cbranch_execz .LBB0_1264
	v_cmp_lt_i32_e32 vcc, 15, v107
	v_mov_b32_e32 v0, v107
	s_and_saveexec_b64 s[4:5], vcc
	s_cbranch_execz .LBB0_1263
	v_cvt_f32_u32_e32 v0, v107
	s_mov_b32 s0, 0x800000
	s_mov_b32 s1, 0x7f800000
	s_mov_b32 s7, 0x40051592
	v_mul_f32_e32 v0, 0x3d800000, v0
	v_cmp_gt_f32_e32 vcc, s0, v0
	s_mov_b32 s0, 0x3f317217
	s_waitcnt lgkmcnt(0)
	v_cndmask_b32_e64 v1, 0, 32, vcc
	v_ldexp_f32 v0, v0, v1
	v_log_f32_e32 v0, v0
	v_mov_b32_e32 v1, 0x41b17218
	v_cndmask_b32_e32 v1, 0, v1, vcc
	v_mul_f32_e32 v2, 0x3f317217, v0
	v_fma_f32 v2, v0, s0, -v2
	v_fmamk_f32 v2, v0, 0x3377d1cf, v2
	v_fmac_f32_e32 v2, 0x3f317217, v0
	v_cmp_lt_f32_e64 s[0:1], |v0|, s1
	s_nop 1
	v_cndmask_b32_e64 v0, v0, v2, s[0:1]
	v_sub_f32_e32 v0, v0, v1
	v_div_scale_f32 v1, s[0:1], s7, s7, v0
	v_rcp_f32_e32 v2, v1
	s_nop 0
	v_fma_f32 v3, -v1, v2, 1.0
	v_fmac_f32_e32 v2, v3, v2
	v_div_scale_f32 v3, vcc, v0, s7, v0
	v_mul_f32_e32 v4, v3, v2
	v_fma_f32 v5, -v1, v4, v3
	v_fmac_f32_e32 v4, v5, v2
	v_fma_f32 v1, -v1, v4, v3
	v_div_fmas_f32 v1, v1, v2, v4
	v_div_fixup_f32 v0, v1, s7, v0
	v_mul_f32_e32 v0, 0x41800000, v0
	v_cvt_i32_f32_e32 v0, v0
	v_min_i32_e32 v0, 15, v0
	v_add_u32_e32 v0, 16, v0

.LBB0_1478:
	s_setprio 0
	s_cmp_gt_i32 s47, 11
	s_cselect_b64 s[0:1], -1, 0
	s_and_b64 s[2:3], s[8:9], s[0:1]
	s_andn2_b64 vcc, exec, s[2:3]
	s_cbranch_vccnz .LBB0_1532
	s_waitcnt vmcnt(0)
	s_waitcnt vmcnt(0) lgkmcnt(0)
	s_barrier
	s_and_saveexec_b64 s[2:3], s[96:97]
	s_cbranch_execz .LBB0_1531
	s_add_i32 s4, 0, 0x24000
	v_mov_b32_e32 v0, s4
	s_waitcnt vmcnt(0) expcnt(0) lgkmcnt(0)
	ds_read_b32 v2, v0
	s_add_i32 s4, 0, 0x24004
	v_mov_b32_e32 v0, s4
	ds_read_b32 v0, v0
	s_waitcnt lgkmcnt(1)
	v_cmp_ne_u32_e32 vcc, 0, v2
	s_cbranch_vccnz .LBB0_1495
	v_readlane_b32 s4, v235, 0
	v_readlane_b32 s5, v235, 1
	s_load_dwordx2 s[8:9], s[4:5], 0x4
	s_add_u32 s4, s44, 0x37440200
	s_addc_u32 s5, s45, 0
	s_add_u32 s6, s44, 0x37440400
	s_addc_u32 s7, s45, 0
	s_waitcnt lgkmcnt(0)
	s_mul_i32 s50, s8, s66
	s_add_u32 s8, s44, 0x37440500
	s_mul_i32 s50, s50, s9
	s_addc_u32 s9, s45, 0
	s_add_u32 s10, s44, 0x37440600
	s_addc_u32 s11, s45, 0
	s_add_u32 s12, s44, 0x37440700
	s_addc_u32 s13, s45, 0
	s_add_u32 s14, s44, 0x37440800
	s_addc_u32 s15, s45, 0
	s_add_u32 s16, s44, 0x37440900
	s_addc_u32 s17, s45, 0
	s_add_u32 s18, s44, 0x37440a00
	s_addc_u32 s19, s45, 0
	s_add_u32 s20, s44, 0x37440b00
	s_addc_u32 s21, s45, 0
	s_add_u32 s22, s44, 0x37440c00
	s_addc_u32 s23, s45, 0
	s_add_u32 s28, s44, 0x37440d00
	s_addc_u32 s29, s45, 0
	s_add_u32 s30, s44, 0x37440e00
	s_addc_u32 s31, s45, 0
	s_add_u32 s34, s44, 0x37440f00
	s_addc_u32 s35, s45, 0
	s_add_u32 s36, s44, 0x37441000
	s_addc_u32 s37, s45, 0
	s_add_u32 s38, s44, 0x37441100
	s_addc_u32 s39, s45, 0
	s_add_u32 s40, s44, 0x37441200
	s_addc_u32 s41, s45, 0
	s_add_u32 s42, s44, 0x37441300
	s_addc_u32 s43, s45, 0
	s_mov_b32 s51, 1
	v_mov_b32_e32 v16, 0
	s_branch .LBB0_1483
